# GEMM phases: one static s_setprio 1 for waves 4-7, all per-block setprio flips removed (on the non-GEMM latency stack)
# speedup vs baseline: 1.0090x; 1.0052x over previous
; #define PG8_STAGE(bufoff, gbase, voff) do { glds_s((const char*)(gbase), (voff), ldsb + (bufoff)); glds_s((const char*)(gbase) + rstep, (voff), ldsb + (bufoff) + 8192u); } while (0)
; #define PG8_WAIT_V(n) asm volatile("s_waitcnt vmcnt(" #n ")" ::: "memory")
; #define PG8_BAR __builtin_amdgcn_s_barrier()
; template <class Epi, class Sched>
; __device__ __forceinline__ void gemm_phase(LAS unsigned char* lds, const Gemm g, const Sched& S, const Epi& E, const int tid) {
;     ...
;     const char* cA = (const char*)g.A + (size_t)cur.pm * tstep + cur.ao; const char* cB = (const char*)g.Bt + (size_t)cur.pn * tstep;
;     PG8_STAGE(PG8_SB(0, 0), cB, voffB); PG8_STAGE(PG8_SB(0, 1), cB + hstep, voffB); PG8_STAGE(PG8_SA(0, 0), cA, voffA); PG8_STAGE(PG8_SA(0, 1), cA + hstep, voffA);
;     if (wr == 1) PG8_BAR;
;     PG8_WAIT_V(2); PG8_BAR;
.LBB0_178:
	s_andn2_b64 vcc, exec, s[0:1]
	s_cbranch_vccnz .LBB0_488
	s_lshl_b64 s[34:35], s[76:77], 9
	s_ashr_i32 s0, s95, 31
	s_mul_i32 s0, s34, s0
	s_mul_hi_u32 s1, s34, s95
	s_ashr_i32 s8, s6, 6
	s_add_i32 s0, s1, s0
	s_lshr_b32 s1, s76, 23
	s_lshl_b32 s49, s8, 10
	s_mul_i32 s4, s1, s95
	s_ashr_i32 s7, s6, 8
	s_waitcnt lgkmcnt(0)
	s_lshl_b64 s[28:29], s[76:77], 7
	s_lshl_b64 s[30:31], s[76:77], 8
	s_add_i32 s49, s49, 0
	s_add_i32 s0, s0, s4
	s_mul_i32 s4, s34, s95
	s_add_u32 s4, s10, s4
	s_addc_u32 s0, s11, s0
	s_add_u32 s2, s4, s2
	v_lshlrev_b32_e32 v3, 6, v3
	s_addc_u32 s3, s0, s3
	s_ashr_i32 s0, s84, 31
	v_lshlrev_b32_e32 v0, 5, v0
	v_sub_u32_e32 v1, v1, v3
	s_mul_i32 s0, s34, s0
	s_mul_hi_u32 s4, s34, s84
	v_and_b32_e32 v0, 32, v0
	v_ashrrev_i16_sdwa v1, v243, sext(v1) dst_sel:DWORD dst_unused:UNUSED_PAD src0_sel:DWORD src1_sel:BYTE_0
	s_add_i32 s0, s4, s0
	s_mul_i32 s1, s1, s84
	v_add_u32_sdwa v0, v0, sext(v1) dst_sel:DWORD dst_unused:UNUSED_PAD src0_sel:DWORD src1_sel:WORD_0
	v_mul_lo_u32 v1, s76, v2
	s_add_i32 s1, s0, s1
	s_mul_i32 s0, s34, s84
	v_add_lshl_u32 v245, v1, v0, 1
	v_mul_lo_u32 v1, v4, s76
	s_add_u32 s0, s12, s0
	v_add_lshl_u32 v246, v1, v0, 1
	s_addc_u32 s1, s13, s1
	s_add_i32 s50, s49, 0x10000
	s_mov_b32 s4, m0
	s_mov_b32 m0, s50
	s_nop 2
	global_load_lds_dwordx4 v246, s[0:1]
	s_mov_b32 m0, s4
	s_add_u32 s4, s0, s28
	s_addc_u32 s5, s1, s29
	s_add_i32 s51, s49, 0x12000
	s_mov_b32 s9, m0
	s_mov_b32 m0, s51
	s_nop 2
	global_load_lds_dwordx4 v246, s[4:5]
	s_mov_b32 m0, s9
	s_add_u32 s4, s0, s30
	s_addc_u32 s5, s1, s31
	s_add_i32 s52, s49, 0x14000
	s_add_u32 s36, s4, s28
	s_mov_b32 s9, m0
	s_mov_b32 m0, s52
	s_nop 2
	global_load_lds_dwordx4 v246, s[4:5]
	s_mov_b32 m0, s9
	s_addc_u32 s37, s5, s29
	s_add_i32 s53, s49, 0x16000
	s_mov_b32 s9, m0
	s_mov_b32 m0, s53
	s_nop 2
	global_load_lds_dwordx4 v246, s[36:37]
	s_mov_b32 m0, s9
	s_add_u32 s36, s2, s28
	s_mov_b32 s9, m0
	s_mov_b32 m0, s49
	s_nop 2
	global_load_lds_dwordx4 v245, s[2:3]
	s_mov_b32 m0, s9
	s_addc_u32 s37, s3, s29
	s_add_i32 s54, s49, 0x2000
	s_mov_b32 s9, m0
	s_mov_b32 m0, s54
	s_nop 2
	global_load_lds_dwordx4 v245, s[36:37]
	s_mov_b32 m0, s9
	s_add_u32 s36, s2, s30
	s_addc_u32 s37, s3, s31
	s_add_i32 s55, s49, 0x4000
	v_writelane_b32 v253, s64, 36
	s_mov_b32 s9, m0
	s_mov_b32 m0, s55
	s_nop 2
	global_load_lds_dwordx4 v245, s[36:37]
	s_mov_b32 m0, s9
	s_add_u32 s38, s36, s28
	s_addc_u32 s39, s37, s29
	v_writelane_b32 v253, s65, 37
	s_add_i32 s56, s49, 0x6000
	s_mov_b32 s9, m0
	s_mov_b32 m0, s56
	s_nop 2
	global_load_lds_dwordx4 v245, s[38:39]
	s_mov_b32 m0, s9
	v_writelane_b32 v253, s62, 27
	s_cmp_eq_u32 s7, 1
	v_mov_b32_e32 v242, 0x80
	v_writelane_b32 v253, s63, 28
	s_cselect_b64 s[36:37], -1, 0
	s_cmp_lg_u32 s7, 1
	s_cbranch_scc1 .LBB0_181
	s_setprio 1
	s_barrier

; #define PG8_STAGE(bufoff, gbase, voff) do { glds_s((const char*)(gbase), (voff), ldsb + (bufoff)); glds_s((const char*)(gbase) + rstep, (voff), ldsb + (bufoff) + 8192u); } while (0)
; #define PG8_LDA(dst, b, h) do { _Pragma("unroll") for (int m = 0; m < 4; ++m) _Pragma("unroll") for (int k = 0; k < 2; ++k) dst[m][k] = *(const LAS bf16x8*)(lds + PG8_SA(b, h) + aoff + m * 2048 + k * 1024); } while (0)
; #define PG8_MMA(ai, bj, At, Bt) do { __builtin_amdgcn_s_setprio(1); _Pragma("unroll") for (int m = 0; m < 4; ++m) _Pragma("unroll") for (int n = 0; n < 2; ++n) _Pragma("unroll") for (int k = 0; k < 2; ++k) \
;         acc[ai][bj][m][n] = __builtin_amdgcn_mfma_f32_16x16x32_bf16(Bt[n][k], At[m][k], acc[ai][bj][m][n], 0, 0, 0); __builtin_amdgcn_s_setprio(0); } while (0)
; #define PG8_WAIT_V(n) asm volatile("s_waitcnt vmcnt(" #n ")" ::: "memory")
; #define PG8_WAIT_L(n) asm volatile("s_waitcnt lgkmcnt(" #n ")" ::: "memory")
; #define PG8_BAR __builtin_amdgcn_s_barrier()
; #define PG8_SCHED __builtin_amdgcn_sched_barrier(0)
; template <class Epi, class Sched>
; __device__ __forceinline__ void gemm_phase(LAS unsigned char* lds, const Gemm g, const Sched& S, const Epi& E, const int tid) {
;     ...
;             if (relax) PG8_WAIT_V(16); else PG8_WAIT_V(8);
;             PG8_WAIT_L(0); PG8_BAR; PG8_MMA(0, 0, At, B0); PG8_MMA(0, 1, At, B1); PG8_BAR; PG8_SCHED;
;             PG8_LDA(At, 0, 1); PG8_STAGE(PG8_SB(0, 0), b2, voffB); PG8_STAGE(PG8_SB(0, 1), b2 + hstep, voffB); PG8_STAGE(PG8_SA(0, 0), a2, voffA);
.LBB0_193:
	s_add_u32 s8, s2, 0x100
	s_waitcnt lgkmcnt(0)
	s_addc_u32 s9, s3, 0
	s_add_u32 s44, s0, 0x100
	s_addc_u32 s45, s1, 0
	s_barrier
	s_waitcnt lgkmcnt(7)
	v_mfma_f32_16x16x32_bf16 v[0:3], v[80:83], v[36:39], 0
	v_mfma_f32_16x16x32_bf16 v[4:7], v[88:91], v[36:39], 0
	s_waitcnt lgkmcnt(5)
	v_mfma_f32_16x16x32_bf16 v[8:11], v[80:83], v[44:47], 0
	v_mfma_f32_16x16x32_bf16 v[12:15], v[88:91], v[44:47], 0
	s_waitcnt lgkmcnt(3)
	v_mfma_f32_16x16x32_bf16 v[16:19], v[80:83], v[52:55], 0
	v_mfma_f32_16x16x32_bf16 v[20:23], v[88:91], v[52:55], 0
	s_waitcnt lgkmcnt(1)
	v_mfma_f32_16x16x32_bf16 v[24:27], v[80:83], v[60:63], 0
	v_mfma_f32_16x16x32_bf16 v[28:31], v[88:91], v[60:63], 0
	v_mfma_f32_16x16x32_bf16 v[0:3], v[84:87], v[40:43], v[0:3]
	v_mfma_f32_16x16x32_bf16 v[4:7], v[92:95], v[40:43], v[4:7]
	v_mfma_f32_16x16x32_bf16 v[8:11], v[84:87], v[48:51], v[8:11]
	v_mfma_f32_16x16x32_bf16 v[12:15], v[92:95], v[48:51], v[12:15]
	v_mfma_f32_16x16x32_bf16 v[16:19], v[84:87], v[56:59], v[16:19]
	v_mfma_f32_16x16x32_bf16 v[20:23], v[92:95], v[56:59], v[20:23]
	s_waitcnt lgkmcnt(0)
	v_mfma_f32_16x16x32_bf16 v[24:27], v[84:87], v[96:99], v[24:27]
	v_mfma_f32_16x16x32_bf16 v[28:31], v[92:95], v[96:99], v[28:31]
	v_mfma_f32_16x16x32_bf16 v[32:35], v[64:67], v[36:39], 0
	v_mfma_f32_16x16x32_bf16 v[36:39], v[72:75], v[36:39], 0
	v_mfma_f32_16x16x32_bf16 v[32:35], v[68:71], v[40:43], v[32:35]
	v_mfma_f32_16x16x32_bf16 v[36:39], v[76:79], v[40:43], v[36:39]
	v_mfma_f32_16x16x32_bf16 v[40:43], v[64:67], v[44:47], 0
	v_mfma_f32_16x16x32_bf16 v[44:47], v[72:75], v[44:47], 0
	v_mfma_f32_16x16x32_bf16 v[40:43], v[68:71], v[48:51], v[40:43]
	v_mfma_f32_16x16x32_bf16 v[44:47], v[76:79], v[48:51], v[44:47]
	v_mfma_f32_16x16x32_bf16 v[48:51], v[64:67], v[52:55], 0
	v_mfma_f32_16x16x32_bf16 v[52:55], v[72:75], v[52:55], 0
	v_mfma_f32_16x16x32_bf16 v[48:51], v[68:71], v[56:59], v[48:51]
	v_mfma_f32_16x16x32_bf16 v[52:55], v[76:79], v[56:59], v[52:55]
	v_mfma_f32_16x16x32_bf16 v[56:59], v[64:67], v[60:63], 0
	v_mfma_f32_16x16x32_bf16 v[60:63], v[72:75], v[60:63], 0
	v_mfma_f32_16x16x32_bf16 v[56:59], v[68:71], v[96:99], v[56:59]
	v_mfma_f32_16x16x32_bf16 v[60:63], v[76:79], v[96:99], v[60:63]
	s_barrier
	ds_read_b128 v[120:123], v250 offset:16384
	s_waitcnt vmcnt(35)
	ds_read_b128 v[124:127], v250 offset:17408
	ds_read_b128 v[112:115], v250 offset:18432
	ds_read_b128 v[116:119], v250 offset:19456
	ds_read_b128 v[104:107], v250 offset:20480
	ds_read_b128 v[108:111], v250 offset:21504
	ds_read_b128 v[96:99], v250 offset:22528
	ds_read_b128 v[100:103], v250 offset:23552
	s_mov_b32 m0, s50
	s_nop 0
	global_load_lds_dwordx4 v246, s[44:45]
	s_add_u32 s44, s44, s28
	s_addc_u32 s45, s45, s29
	s_add_u32 s85, s0, s30
	s_addc_u32 s96, s1, s31
	s_mov_b32 m0, s51
	s_nop 0
	global_load_lds_dwordx4 v246, s[44:45]
	s_add_u32 s44, s85, 0x100
	s_addc_u32 s45, s96, 0
	s_mov_b32 m0, s52
	s_nop 0
	global_load_lds_dwordx4 v246, s[44:45]
	s_add_u32 s44, s44, s28
	s_addc_u32 s45, s45, s29
	s_mov_b32 m0, s53
	s_nop 0
	global_load_lds_dwordx4 v246, s[44:45]
	s_nop 0
	s_mov_b32 m0, s49
	s_nop 0
	global_load_lds_dwordx4 v245, s[8:9]
	s_add_u32 s8, s8, s28
	s_addc_u32 s9, s9, s29
	s_mov_b32 m0, s54
	s_nop 0
	global_load_lds_dwordx4 v245, s[8:9]
	s_and_b64 vcc, exec, s[6:7]
	s_cbranch_vccz .LBB0_215
	s_waitcnt vmcnt(16)
	s_cbranch_execnz .LBB0_196

; #define PG8_STAGE(bufoff, gbase, voff) do { glds_s((const char*)(gbase), (voff), ldsb + (bufoff)); glds_s((const char*)(gbase) + rstep, (voff), ldsb + (bufoff) + 8192u); } while (0)
; #define PG8_LDA(dst, b, h) do { _Pragma("unroll") for (int m = 0; m < 4; ++m) _Pragma("unroll") for (int k = 0; k < 2; ++k) dst[m][k] = *(const LAS bf16x8*)(lds + PG8_SA(b, h) + aoff + m * 2048 + k * 1024); } while (0)
; #define PG8_LDB(dst, b, h) do { _Pragma("unroll") for (int n = 0; n < 2; ++n) _Pragma("unroll") for (int k = 0; k < 2; ++k) dst[n][k] = *(const LAS bf16x8*)(lds + PG8_SB(b, h) + boff + n * 2048 + k * 1024); } while (0)
; #define PG8_MMA(ai, bj, At, Bt) do { __builtin_amdgcn_s_setprio(1); _Pragma("unroll") for (int m = 0; m < 4; ++m) _Pragma("unroll") for (int n = 0; n < 2; ++n) _Pragma("unroll") for (int k = 0; k < 2; ++k) \
;         acc[ai][bj][m][n] = __builtin_amdgcn_mfma_f32_16x16x32_bf16(Bt[n][k], At[m][k], acc[ai][bj][m][n], 0, 0, 0); __builtin_amdgcn_s_setprio(0); } while (0)
; #define PG8_WAIT_V(n) asm volatile("s_waitcnt vmcnt(" #n ")" ::: "memory")
; #define PG8_WAIT_L(n) asm volatile("s_waitcnt lgkmcnt(" #n ")" ::: "memory")
; #define PG8_BAR __builtin_amdgcn_s_barrier()
; #define PG8_SCHED __builtin_amdgcn_sched_barrier(0)
; template <class Epi, class Sched>
; __device__ __forceinline__ void gemm_phase(LAS unsigned char* lds, const Gemm g, const Sched& S, const Epi& E, const int tid) {
;     ...
;             if (relax) PG8_WAIT_V(16); else PG8_WAIT_V(8);
;             PG8_WAIT_L(0); PG8_BAR; PG8_MMA(1, 0, At, B0); PG8_MMA(1, 1, At, B1); PG8_BAR; PG8_SCHED;
;             PG8_LDB(B0, 1, 0); PG8_LDB(B1, 1, 1); PG8_SCHED; PG8_LDA(At, 1, 0); PG8_STAGE(PG8_SA(0, 1), a2 + hstep, voffA);
.LBB0_196:
	s_waitcnt lgkmcnt(0)
	s_barrier
	s_waitcnt vmcnt(34) lgkmcnt(7)
	v_mfma_f32_16x16x32_bf16 v[128:131], v[80:83], v[120:123], 0
	s_waitcnt lgkmcnt(6)
	v_mfma_f32_16x16x32_bf16 v[150:153], v[84:87], v[124:127], v[128:131]
	v_mfma_f32_16x16x32_bf16 v[128:131], v[88:91], v[120:123], 0
	v_mfma_f32_16x16x32_bf16 v[154:157], v[92:95], v[124:127], v[128:131]
	s_waitcnt lgkmcnt(5)
	v_mfma_f32_16x16x32_bf16 v[128:131], v[80:83], v[112:115], 0
	s_waitcnt lgkmcnt(4)
	v_mfma_f32_16x16x32_bf16 v[158:161], v[84:87], v[116:119], v[128:131]
	v_mfma_f32_16x16x32_bf16 v[128:131], v[88:91], v[112:115], 0
	v_mfma_f32_16x16x32_bf16 v[162:165], v[92:95], v[116:119], v[128:131]
	s_waitcnt lgkmcnt(3)
	v_mfma_f32_16x16x32_bf16 v[128:131], v[80:83], v[104:107], 0
	s_waitcnt lgkmcnt(1)
	v_mfma_f32_16x16x32_bf16 v[80:83], v[80:83], v[96:99], 0
	v_mfma_f32_16x16x32_bf16 v[166:169], v[84:87], v[108:111], v[128:131]
	v_mfma_f32_16x16x32_bf16 v[128:131], v[88:91], v[104:107], 0
	s_waitcnt lgkmcnt(0)
	v_mfma_f32_16x16x32_bf16 v[174:177], v[84:87], v[100:103], v[80:83]
	v_mfma_f32_16x16x32_bf16 v[80:83], v[88:91], v[96:99], 0
	v_mfma_f32_16x16x32_bf16 v[170:173], v[92:95], v[108:111], v[128:131]
	v_mfma_f32_16x16x32_bf16 v[86:89], v[92:95], v[100:103], v[80:83]
	v_mfma_f32_16x16x32_bf16 v[80:83], v[64:67], v[120:123], 0
	v_mfma_f32_16x16x32_bf16 v[178:181], v[68:71], v[124:127], v[80:83]
	v_mfma_f32_16x16x32_bf16 v[80:83], v[72:75], v[120:123], 0
	v_mfma_f32_16x16x32_bf16 v[182:185], v[76:79], v[124:127], v[80:83]
	v_mfma_f32_16x16x32_bf16 v[80:83], v[64:67], v[112:115], 0
	v_mfma_f32_16x16x32_bf16 v[186:189], v[68:71], v[116:119], v[80:83]
	v_mfma_f32_16x16x32_bf16 v[80:83], v[72:75], v[112:115], 0
	v_mfma_f32_16x16x32_bf16 v[190:193], v[76:79], v[116:119], v[80:83]
	v_mfma_f32_16x16x32_bf16 v[80:83], v[64:67], v[104:107], 0
	v_mfma_f32_16x16x32_bf16 v[64:67], v[64:67], v[96:99], 0
	v_mfma_f32_16x16x32_bf16 v[194:197], v[68:71], v[108:111], v[80:83]
	v_mfma_f32_16x16x32_bf16 v[80:83], v[72:75], v[104:107], 0
	v_mfma_f32_16x16x32_bf16 v[202:205], v[68:71], v[100:103], v[64:67]
	v_mfma_f32_16x16x32_bf16 v[64:67], v[72:75], v[96:99], 0
	v_mfma_f32_16x16x32_bf16 v[198:201], v[76:79], v[108:111], v[80:83]
	v_mfma_f32_16x16x32_bf16 v[206:209], v[76:79], v[100:103], v[64:67]
	s_barrier
	v_add_u32_e32 v252, 0x18000, v249
	v_add_u32_e32 v240, 0x1c000, v249
	s_nop 1
	ds_read_b128 v[66:69], v252
	ds_read_b128 v[74:77], v252 offset:1024
	ds_read_b128 v[226:229], v252 offset:2048
	ds_read_b128 v[230:233], v252 offset:3072
	ds_read_b128 v[210:213], v240
	ds_read_b128 v[214:217], v240 offset:1024
	ds_read_b128 v[218:221], v240 offset:2048
	ds_read_b128 v[222:225], v240 offset:3072
	ds_read_b128 v[122:125], v250 offset:32768
	s_waitcnt vmcnt(33)
	ds_read_b128 v[130:133], v250 offset:33792
	ds_read_b128 v[106:109], v250 offset:34816
	ds_read_b128 v[114:117], v250 offset:35840
	ds_read_b128 v[90:93], v250 offset:36864
	ds_read_b128 v[98:101], v250 offset:37888
	ds_read_b128 v[70:73], v250 offset:38912
	ds_read_b128 v[78:81], v250 offset:39936
	s_add_u32 s8, s40, 0x100
	s_addc_u32 s9, s41, 0
	s_mov_b32 m0, s55
	s_nop 0
	global_load_lds_dwordx4 v245, s[8:9]
	s_add_u32 s8, s8, s28
	s_addc_u32 s9, s9, s29
	s_mov_b32 m0, s56
	s_nop 0
	global_load_lds_dwordx4 v245, s[8:9]
	s_and_b64 vcc, exec, s[6:7]
	s_cbranch_vccz .LBB0_216
	s_waitcnt vmcnt(16)
	s_cbranch_execnz .LBB0_199

; #define PG8_STAGE(bufoff, gbase, voff) do { glds_s((const char*)(gbase), (voff), ldsb + (bufoff)); glds_s((const char*)(gbase) + rstep, (voff), ldsb + (bufoff) + 8192u); } while (0)
; #define PG8_LDA(dst, b, h) do { _Pragma("unroll") for (int m = 0; m < 4; ++m) _Pragma("unroll") for (int k = 0; k < 2; ++k) dst[m][k] = *(const LAS bf16x8*)(lds + PG8_SA(b, h) + aoff + m * 2048 + k * 1024); } while (0)
; #define PG8_MMA(ai, bj, At, Bt) do { __builtin_amdgcn_s_setprio(1); _Pragma("unroll") for (int m = 0; m < 4; ++m) _Pragma("unroll") for (int n = 0; n < 2; ++n) _Pragma("unroll") for (int k = 0; k < 2; ++k) \
;         acc[ai][bj][m][n] = __builtin_amdgcn_mfma_f32_16x16x32_bf16(Bt[n][k], At[m][k], acc[ai][bj][m][n], 0, 0, 0); __builtin_amdgcn_s_setprio(0); } while (0)
; #define PG8_WAIT_V(n) asm volatile("s_waitcnt vmcnt(" #n ")" ::: "memory")
; #define PG8_WAIT_L(n) asm volatile("s_waitcnt lgkmcnt(" #n ")" ::: "memory")
; #define PG8_BAR __builtin_amdgcn_s_barrier()
; #define PG8_SCHED __builtin_amdgcn_sched_barrier(0)
; template <class Epi, class Sched>
; __device__ __forceinline__ void gemm_phase(LAS unsigned char* lds, const Gemm g, const Sched& S, const Epi& E, const int tid) {
;     ...
;             if (relax) PG8_WAIT_V(16); else PG8_WAIT_V(8);
;             PG8_WAIT_L(0); PG8_BAR; PG8_MMA(0, 0, At, B0); PG8_MMA(0, 1, At, B1); PG8_BAR; PG8_SCHED;
;             PG8_LDA(At, 1, 1); PG8_STAGE(PG8_SB(1, 0), b3, voffB); PG8_STAGE(PG8_SB(1, 1), b3 + hstep, voffB); PG8_STAGE(PG8_SA(1, 0), a3, voffA);
;             PG8_WAIT_V(8); PG8_WAIT_L(0); PG8_BAR; PG8_MMA(1, 0, At, B0); PG8_MMA(1, 1, At, B1); PG8_BAR; PG8_SCHED;
.LBB0_199:
	s_add_u32 s2, s2, 0x180
	s_waitcnt lgkmcnt(0)
	s_addc_u32 s3, s3, 0
	s_add_u32 s6, s0, 0x180
	s_addc_u32 s7, s1, 0
	s_barrier
	s_waitcnt lgkmcnt(7)
	v_mfma_f32_16x16x32_bf16 v[0:3], v[66:69], v[122:125], v[0:3]
	s_waitcnt lgkmcnt(6)
	v_mfma_f32_16x16x32_bf16 v[142:145], v[74:77], v[130:133], v[0:3]
	v_mfma_f32_16x16x32_bf16 v[0:3], v[226:229], v[122:125], v[4:7]
	s_waitcnt vmcnt(32)
	v_mfma_f32_16x16x32_bf16 v[134:137], v[230:233], v[130:133], v[0:3]
	s_waitcnt lgkmcnt(5)
	v_mfma_f32_16x16x32_bf16 v[0:3], v[66:69], v[106:109], v[8:11]
	s_waitcnt lgkmcnt(4)
	v_mfma_f32_16x16x32_bf16 v[126:129], v[74:77], v[114:117], v[0:3]
	v_mfma_f32_16x16x32_bf16 v[0:3], v[226:229], v[106:109], v[12:15]
	v_mfma_f32_16x16x32_bf16 v[118:121], v[230:233], v[114:117], v[0:3]
	s_waitcnt lgkmcnt(3)
	v_mfma_f32_16x16x32_bf16 v[0:3], v[66:69], v[90:93], v[16:19]
	s_waitcnt lgkmcnt(2)
	v_mfma_f32_16x16x32_bf16 v[110:113], v[74:77], v[98:101], v[0:3]
	v_mfma_f32_16x16x32_bf16 v[0:3], v[226:229], v[90:93], v[20:23]
	v_mfma_f32_16x16x32_bf16 v[102:105], v[230:233], v[98:101], v[0:3]
	s_waitcnt lgkmcnt(1)
	v_mfma_f32_16x16x32_bf16 v[0:3], v[66:69], v[70:73], v[24:27]
	s_waitcnt lgkmcnt(0)
	v_mfma_f32_16x16x32_bf16 v[94:97], v[74:77], v[78:81], v[0:3]
	v_mfma_f32_16x16x32_bf16 v[0:3], v[226:229], v[70:73], v[28:31]
	v_mfma_f32_16x16x32_bf16 v[82:85], v[230:233], v[78:81], v[0:3]
	v_mfma_f32_16x16x32_bf16 v[0:3], v[210:213], v[122:125], v[32:35]
	v_mfma_f32_16x16x32_bf16 v[146:149], v[214:217], v[130:133], v[0:3]
	v_mfma_f32_16x16x32_bf16 v[0:3], v[218:221], v[122:125], v[36:39]
	v_mfma_f32_16x16x32_bf16 v[138:141], v[222:225], v[130:133], v[0:3]
	v_mfma_f32_16x16x32_bf16 v[0:3], v[210:213], v[106:109], v[40:43]
	v_mfma_f32_16x16x32_bf16 v[130:133], v[214:217], v[114:117], v[0:3]
	v_mfma_f32_16x16x32_bf16 v[0:3], v[218:221], v[106:109], v[44:47]
	v_mfma_f32_16x16x32_bf16 v[122:125], v[222:225], v[114:117], v[0:3]
	v_mfma_f32_16x16x32_bf16 v[0:3], v[210:213], v[90:93], v[48:51]
	v_mfma_f32_16x16x32_bf16 v[114:117], v[214:217], v[98:101], v[0:3]
	v_mfma_f32_16x16x32_bf16 v[0:3], v[218:221], v[90:93], v[52:55]
	v_mfma_f32_16x16x32_bf16 v[106:109], v[222:225], v[98:101], v[0:3]
	v_mfma_f32_16x16x32_bf16 v[0:3], v[210:213], v[70:73], v[56:59]
	v_mfma_f32_16x16x32_bf16 v[98:101], v[214:217], v[78:81], v[0:3]
	v_mfma_f32_16x16x32_bf16 v[0:3], v[218:221], v[70:73], v[60:63]
	v_mfma_f32_16x16x32_bf16 v[90:93], v[222:225], v[78:81], v[0:3]
	s_barrier
	s_nop 4
	ds_read_b128 v[0:3], v250 offset:49152
	ds_read_b128 v[4:7], v250 offset:50176
	ds_read_b128 v[8:11], v250 offset:51200
	ds_read_b128 v[12:15], v250 offset:52224
	ds_read_b128 v[16:19], v250 offset:53248
	ds_read_b128 v[26:29], v250 offset:54272
	ds_read_b128 v[236:239], v250 offset:55296
	ds_read_b128 v[20:23], v250 offset:56320
	s_mov_b32 m0, s59
	s_nop 0
	global_load_lds_dwordx4 v246, s[6:7]
	s_add_u32 s6, s6, s28
	s_addc_u32 s7, s7, s29
	s_mov_b32 m0, s60
	s_nop 0
	global_load_lds_dwordx4 v246, s[6:7]
	s_add_u32 s6, s85, 0x180
	s_addc_u32 s7, s96, 0
	s_mov_b32 m0, s63
	s_nop 0
	global_load_lds_dwordx4 v246, s[6:7]
	s_add_u32 s6, s6, s28
	s_addc_u32 s7, s7, s29
	s_mov_b32 m0, s64
	s_nop 0
	global_load_lds_dwordx4 v246, s[6:7]
	s_mov_b32 m0, s61
	s_nop 0
	global_load_lds_dwordx4 v245, s[2:3]
	s_add_u32 s6, s2, s28
	s_addc_u32 s7, s3, s29
	s_mov_b32 m0, s62
	s_nop 0
	global_load_lds_dwordx4 v245, s[6:7]
	s_waitcnt vmcnt(8)
	s_waitcnt lgkmcnt(0)
	s_barrier
	s_waitcnt lgkmcnt(7)
	v_mfma_f32_16x16x32_bf16 v[30:33], v[66:69], v[0:3], v[150:153]
	s_waitcnt lgkmcnt(6)
	v_mfma_f32_16x16x32_bf16 v[78:81], v[74:77], v[4:7], v[30:33]
	v_mfma_f32_16x16x32_bf16 v[30:33], v[226:229], v[0:3], v[154:157]
	v_mfma_f32_16x16x32_bf16 v[70:73], v[230:233], v[4:7], v[30:33]
	s_waitcnt lgkmcnt(5)
	v_mfma_f32_16x16x32_bf16 v[30:33], v[66:69], v[8:11], v[158:161]
	s_waitcnt lgkmcnt(4)
	v_mfma_f32_16x16x32_bf16 v[62:65], v[74:77], v[12:15], v[30:33]
	v_mfma_f32_16x16x32_bf16 v[30:33], v[226:229], v[8:11], v[162:165]
	v_mfma_f32_16x16x32_bf16 v[54:57], v[230:233], v[12:15], v[30:33]
	s_waitcnt lgkmcnt(3)
	v_mfma_f32_16x16x32_bf16 v[30:33], v[66:69], v[16:19], v[166:169]
	s_waitcnt lgkmcnt(2)
	v_mfma_f32_16x16x32_bf16 v[46:49], v[74:77], v[26:29], v[30:33]
	v_mfma_f32_16x16x32_bf16 v[30:33], v[226:229], v[16:19], v[170:173]
	v_mfma_f32_16x16x32_bf16 v[38:41], v[230:233], v[26:29], v[30:33]
	s_waitcnt lgkmcnt(1)
	v_mfma_f32_16x16x32_bf16 v[30:33], v[66:69], v[236:239], v[174:177]
	v_mfma_f32_16x16x32_bf16 v[34:37], v[226:229], v[236:239], v[86:89]
	s_waitcnt lgkmcnt(0)
	v_mfma_f32_16x16x32_bf16 v[30:33], v[74:77], v[20:23], v[30:33]
	v_mfma_f32_16x16x32_bf16 v[226:229], v[230:233], v[20:23], v[34:37]
	v_mfma_f32_16x16x32_bf16 v[34:37], v[210:213], v[0:3], v[178:181]
	v_mfma_f32_16x16x32_bf16 v[0:3], v[218:221], v[0:3], v[182:185]
	v_mfma_f32_16x16x32_bf16 v[74:77], v[222:225], v[4:7], v[0:3]
	v_mfma_f32_16x16x32_bf16 v[0:3], v[210:213], v[8:11], v[186:189]
	v_mfma_f32_16x16x32_bf16 v[66:69], v[214:217], v[12:15], v[0:3]
	v_mfma_f32_16x16x32_bf16 v[0:3], v[218:221], v[8:11], v[190:193]
	v_mfma_f32_16x16x32_bf16 v[58:61], v[222:225], v[12:15], v[0:3]
	v_mfma_f32_16x16x32_bf16 v[0:3], v[210:213], v[16:19], v[194:197]
	v_mfma_f32_16x16x32_bf16 v[50:53], v[214:217], v[26:29], v[0:3]
	v_mfma_f32_16x16x32_bf16 v[0:3], v[218:221], v[16:19], v[198:201]
	v_mfma_f32_16x16x32_bf16 v[42:45], v[222:225], v[26:29], v[0:3]
	v_mfma_f32_16x16x32_bf16 v[0:3], v[210:213], v[236:239], v[202:205]
	v_mfma_f32_16x16x32_bf16 v[86:89], v[214:217], v[4:7], v[34:37]
	v_mfma_f32_16x16x32_bf16 v[34:37], v[214:217], v[20:23], v[0:3]
	v_mfma_f32_16x16x32_bf16 v[0:3], v[218:221], v[236:239], v[206:209]
	v_mfma_f32_16x16x32_bf16 v[26:29], v[222:225], v[20:23], v[0:3]
	s_barrier
	s_add_u32 s85, s0, 0x200
	s_addc_u32 s96, s1, 0
	s_mov_b32 s97, 4
; #define PG8_STAGE(bufoff, gbase, voff) do { glds_s((const char*)(gbase), (voff), ldsb + (bufoff)); glds_s((const char*)(gbase) + rstep, (voff), ldsb + (bufoff) + 8192u); } while (0)
; #define PG8_LDA(dst, b, h) do { _Pragma("unroll") for (int m = 0; m < 4; ++m) _Pragma("unroll") for (int k = 0; k < 2; ++k) dst[m][k] = *(const LAS bf16x8*)(lds + PG8_SA(b, h) + aoff + m * 2048 + k * 1024); } while (0)
; #define PG8_LDB(dst, b, h) do { _Pragma("unroll") for (int n = 0; n < 2; ++n) _Pragma("unroll") for (int k = 0; k < 2; ++k) dst[n][k] = *(const LAS bf16x8*)(lds + PG8_SB(b, h) + boff + n * 2048 + k * 1024); } while (0)
; #define PG8_MMA(ai, bj, At, Bt) do { __builtin_amdgcn_s_setprio(1); _Pragma("unroll") for (int m = 0; m < 4; ++m) _Pragma("unroll") for (int n = 0; n < 2; ++n) _Pragma("unroll") for (int k = 0; k < 2; ++k) \
;         acc[ai][bj][m][n] = __builtin_amdgcn_mfma_f32_16x16x32_bf16(Bt[n][k], At[m][k], acc[ai][bj][m][n], 0, 0, 0); __builtin_amdgcn_s_setprio(0); } while (0)
; #define PG8_WAIT_V(n) asm volatile("s_waitcnt vmcnt(" #n ")" ::: "memory")
; #define PG8_WAIT_L(n) asm volatile("s_waitcnt lgkmcnt(" #n ")" ::: "memory")
; #define PG8_BAR __builtin_amdgcn_s_barrier()
; #define PG8_SCHED __builtin_amdgcn_sched_barrier(0)
; template <class Epi, class Sched>
; __device__ __forceinline__ void gemm_phase(LAS unsigned char* lds, const Gemm g, const Sched& S, const Epi& E, const int tid) {
;     ...
;         for (int t = 0; t < nt; t += 2) {
;             const bool last = (t == nt - 2);
;             const char* a1 = cA + (size_t)(t + 1) * kstep;
;             const char* a2 = last ? nA : cA + (size_t)(t + 2) * kstep; const char* b2 = last ? nB : cB + (size_t)(t + 2) * kstep;
;             const char* a3 = a2 + kstep; const char* b3 = b2 + kstep;
;             const bool relax = (t == 0) && (ui > 0);
;             PG8_LDB(B0, 0, 0); PG8_LDB(B1, 0, 1); PG8_SCHED; PG8_LDA(At, 0, 0); if (!relax) PG8_STAGE(PG8_SA(1, 1), a1 + hstep, voffA);
;             if (relax) PG8_WAIT_V(16); else PG8_WAIT_V(8);
;             PG8_WAIT_L(0); PG8_BAR; PG8_MMA(0, 0, At, B0); PG8_MMA(0, 1, At, B1); PG8_BAR; PG8_SCHED;
;             PG8_LDA(At, 0, 1); PG8_STAGE(PG8_SB(0, 0), b2, voffB); PG8_STAGE(PG8_SB(0, 1), b2 + hstep, voffB); PG8_STAGE(PG8_SA(0, 0), a2, voffA);
.LBB0_200:
	s_add_u32 s0, s2, 0x80
	s_nop 0
	ds_read_b128 v[0:3], v234
	ds_read_b128 v[4:7], v234 offset:1024
	ds_read_b128 v[8:11], v234 offset:2048
	ds_read_b128 v[12:15], v234 offset:3072
	ds_read_b128 v[16:19], v251
	ds_read_b128 v[20:23], v251 offset:1024
	ds_read_b128 v[150:153], v251 offset:2048
	ds_read_b128 v[154:157], v251 offset:3072
	s_addc_u32 s1, s3, 0
	s_cmp_eq_u32 s42, s97
	s_cselect_b32 s8, s80, s0
	s_cselect_b32 s9, s81, s1
	s_cselect_b32 s40, s82, s85
	s_cselect_b32 s41, s83, s96
	s_add_u32 s0, s8, 0x80
	s_addc_u32 s1, s9, 0
	s_add_u32 s6, s40, 0x80
	s_addc_u32 s7, s41, 0
	ds_read_b128 v[158:161], v250
	ds_read_b128 v[162:165], v250 offset:1024
	ds_read_b128 v[166:169], v250 offset:2048
	ds_read_b128 v[170:173], v250 offset:3072
	ds_read_b128 v[174:177], v250 offset:4096
	ds_read_b128 v[178:181], v250 offset:5120
	ds_read_b128 v[182:185], v250 offset:6144
	ds_read_b128 v[186:189], v250 offset:7168
	s_add_u32 s44, s2, s30
	s_addc_u32 s45, s3, s31
	s_mov_b32 m0, s65
	s_nop 0
	global_load_lds_dwordx4 v245, s[44:45]
	s_add_u32 s44, s44, s28
	s_addc_u32 s45, s45, s29
	s_mov_b32 m0, s86
	s_nop 0
	global_load_lds_dwordx4 v245, s[44:45]
	s_waitcnt vmcnt(8)
	s_waitcnt lgkmcnt(0)
	s_barrier
	s_waitcnt lgkmcnt(7)
	v_mfma_f32_16x16x32_bf16 v[142:145], v[0:3], v[158:161], v[142:145]
	v_mfma_f32_16x16x32_bf16 v[134:137], v[8:11], v[158:161], v[134:137]
	s_waitcnt lgkmcnt(5)
	v_mfma_f32_16x16x32_bf16 v[126:129], v[0:3], v[166:169], v[126:129]
	v_mfma_f32_16x16x32_bf16 v[118:121], v[8:11], v[166:169], v[118:121]
	s_waitcnt lgkmcnt(3)
	v_mfma_f32_16x16x32_bf16 v[110:113], v[0:3], v[174:177], v[110:113]
	v_mfma_f32_16x16x32_bf16 v[102:105], v[8:11], v[174:177], v[102:105]
	s_waitcnt lgkmcnt(1)
	v_mfma_f32_16x16x32_bf16 v[94:97], v[0:3], v[182:185], v[94:97]
	v_mfma_f32_16x16x32_bf16 v[82:85], v[8:11], v[182:185], v[82:85]
	v_mfma_f32_16x16x32_bf16 v[142:145], v[4:7], v[162:165], v[142:145]
	v_mfma_f32_16x16x32_bf16 v[134:137], v[12:15], v[162:165], v[134:137]
	v_mfma_f32_16x16x32_bf16 v[126:129], v[4:7], v[170:173], v[126:129]
	v_mfma_f32_16x16x32_bf16 v[118:121], v[12:15], v[170:173], v[118:121]
	v_mfma_f32_16x16x32_bf16 v[110:113], v[4:7], v[178:181], v[110:113]
	v_mfma_f32_16x16x32_bf16 v[102:105], v[12:15], v[178:181], v[102:105]
	s_waitcnt lgkmcnt(0)
	v_mfma_f32_16x16x32_bf16 v[94:97], v[4:7], v[186:189], v[94:97]
	v_mfma_f32_16x16x32_bf16 v[82:85], v[12:15], v[186:189], v[82:85]
	v_mfma_f32_16x16x32_bf16 v[146:149], v[16:19], v[158:161], v[146:149]
	v_mfma_f32_16x16x32_bf16 v[138:141], v[150:153], v[158:161], v[138:141]
	v_mfma_f32_16x16x32_bf16 v[130:133], v[16:19], v[166:169], v[130:133]
	v_mfma_f32_16x16x32_bf16 v[122:125], v[150:153], v[166:169], v[122:125]
	v_mfma_f32_16x16x32_bf16 v[114:117], v[16:19], v[174:177], v[114:117]
	v_mfma_f32_16x16x32_bf16 v[106:109], v[150:153], v[174:177], v[106:109]
	v_mfma_f32_16x16x32_bf16 v[98:101], v[16:19], v[182:185], v[98:101]
	v_mfma_f32_16x16x32_bf16 v[90:93], v[150:153], v[182:185], v[90:93]
	v_mfma_f32_16x16x32_bf16 v[146:149], v[20:23], v[162:165], v[146:149]
	v_mfma_f32_16x16x32_bf16 v[138:141], v[154:157], v[162:165], v[138:141]
	v_mfma_f32_16x16x32_bf16 v[130:133], v[20:23], v[170:173], v[130:133]
	v_mfma_f32_16x16x32_bf16 v[122:125], v[154:157], v[170:173], v[122:125]
	v_mfma_f32_16x16x32_bf16 v[114:117], v[20:23], v[178:181], v[114:117]
	v_mfma_f32_16x16x32_bf16 v[106:109], v[154:157], v[178:181], v[106:109]
	v_mfma_f32_16x16x32_bf16 v[98:101], v[20:23], v[186:189], v[98:101]
	v_mfma_f32_16x16x32_bf16 v[90:93], v[154:157], v[186:189], v[90:93]
	s_barrier
	s_add_u32 s44, s40, s28
	ds_read_b128 v[158:161], v250 offset:16384
	ds_read_b128 v[162:165], v250 offset:17408
	ds_read_b128 v[166:169], v250 offset:18432
	ds_read_b128 v[170:173], v250 offset:19456
	ds_read_b128 v[174:177], v250 offset:20480
	ds_read_b128 v[178:181], v250 offset:21504
	ds_read_b128 v[182:185], v250 offset:22528
	ds_read_b128 v[186:189], v250 offset:23552
	s_addc_u32 s45, s41, s29
	s_mov_b32 m0, s50
	s_nop 0
	global_load_lds_dwordx4 v246, s[40:41]
	s_add_u32 s40, s40, s30
	s_mov_b32 m0, s51
	s_nop 0
	global_load_lds_dwordx4 v246, s[44:45]
	s_addc_u32 s41, s41, s31
	s_mov_b32 m0, s52
	s_nop 0
	global_load_lds_dwordx4 v246, s[40:41]
	s_add_u32 s44, s40, s28
	s_addc_u32 s45, s41, s29
	s_mov_b32 m0, s53
	s_nop 0
	global_load_lds_dwordx4 v246, s[44:45]
	s_add_u32 s44, s8, s28
	s_mov_b32 m0, s49
	s_nop 0
	global_load_lds_dwordx4 v245, s[8:9]
	s_addc_u32 s45, s9, s29
	s_mov_b32 m0, s54
	s_nop 0
	global_load_lds_dwordx4 v245, s[44:45]
	s_waitcnt vmcnt(8)
	s_waitcnt lgkmcnt(0)
	s_barrier
; #define PG8_STAGE(bufoff, gbase, voff) do { glds_s((const char*)(gbase), (voff), ldsb + (bufoff)); glds_s((const char*)(gbase) + rstep, (voff), ldsb + (bufoff) + 8192u); } while (0)
; #define PG8_LDA(dst, b, h) do { _Pragma("unroll") for (int m = 0; m < 4; ++m) _Pragma("unroll") for (int k = 0; k < 2; ++k) dst[m][k] = *(const LAS bf16x8*)(lds + PG8_SA(b, h) + aoff + m * 2048 + k * 1024); } while (0)
; #define PG8_LDB(dst, b, h) do { _Pragma("unroll") for (int n = 0; n < 2; ++n) _Pragma("unroll") for (int k = 0; k < 2; ++k) dst[n][k] = *(const LAS bf16x8*)(lds + PG8_SB(b, h) + boff + n * 2048 + k * 1024); } while (0)
; #define PG8_MMA(ai, bj, At, Bt) do { __builtin_amdgcn_s_setprio(1); _Pragma("unroll") for (int m = 0; m < 4; ++m) _Pragma("unroll") for (int n = 0; n < 2; ++n) _Pragma("unroll") for (int k = 0; k < 2; ++k) \
;         acc[ai][bj][m][n] = __builtin_amdgcn_mfma_f32_16x16x32_bf16(Bt[n][k], At[m][k], acc[ai][bj][m][n], 0, 0, 0); __builtin_amdgcn_s_setprio(0); } while (0)
; #define PG8_WAIT_V(n) asm volatile("s_waitcnt vmcnt(" #n ")" ::: "memory")
; #define PG8_WAIT_L(n) asm volatile("s_waitcnt lgkmcnt(" #n ")" ::: "memory")
; #define PG8_BAR __builtin_amdgcn_s_barrier()
; #define PG8_SCHED __builtin_amdgcn_sched_barrier(0)
; template <class Epi, class Sched>
; __device__ __forceinline__ void gemm_phase(LAS unsigned char* lds, const Gemm g, const Sched& S, const Epi& E, const int tid) {
;     ...
;             if (relax) PG8_WAIT_V(16); else PG8_WAIT_V(8);
;             PG8_WAIT_L(0); PG8_BAR; PG8_MMA(1, 0, At, B0); PG8_MMA(1, 1, At, B1); PG8_BAR; PG8_SCHED;
;             PG8_LDB(B0, 1, 0); PG8_LDB(B1, 1, 1); PG8_SCHED; PG8_LDA(At, 1, 0); PG8_STAGE(PG8_SA(0, 1), a2 + hstep, voffA);
;             if (relax) PG8_WAIT_V(16); else PG8_WAIT_V(8);
;             PG8_WAIT_L(0); PG8_BAR; PG8_MMA(0, 0, At, B0); PG8_MMA(0, 1, At, B1); PG8_BAR; PG8_SCHED;
;             PG8_LDA(At, 1, 1); PG8_STAGE(PG8_SB(1, 0), b3, voffB); PG8_STAGE(PG8_SB(1, 1), b3 + hstep, voffB); PG8_STAGE(PG8_SA(1, 0), a3, voffA);
;             PG8_WAIT_V(8); PG8_WAIT_L(0); PG8_BAR; PG8_MMA(1, 0, At, B0); PG8_MMA(1, 1, At, B1); PG8_BAR; PG8_SCHED;
	s_waitcnt lgkmcnt(7)
	v_mfma_f32_16x16x32_bf16 v[78:81], v[0:3], v[158:161], v[78:81]
	v_mfma_f32_16x16x32_bf16 v[70:73], v[8:11], v[158:161], v[70:73]
	s_waitcnt lgkmcnt(5)
	v_mfma_f32_16x16x32_bf16 v[62:65], v[0:3], v[166:169], v[62:65]
	v_mfma_f32_16x16x32_bf16 v[54:57], v[8:11], v[166:169], v[54:57]
	s_waitcnt lgkmcnt(3)
	v_mfma_f32_16x16x32_bf16 v[46:49], v[0:3], v[174:177], v[46:49]
	v_mfma_f32_16x16x32_bf16 v[38:41], v[8:11], v[174:177], v[38:41]
	s_waitcnt lgkmcnt(1)
	v_mfma_f32_16x16x32_bf16 v[0:3], v[0:3], v[182:185], v[30:33]
	v_mfma_f32_16x16x32_bf16 v[78:81], v[4:7], v[162:165], v[78:81]
	v_mfma_f32_16x16x32_bf16 v[70:73], v[12:15], v[162:165], v[70:73]
	v_mfma_f32_16x16x32_bf16 v[62:65], v[4:7], v[170:173], v[62:65]
	v_mfma_f32_16x16x32_bf16 v[54:57], v[12:15], v[170:173], v[54:57]
	v_mfma_f32_16x16x32_bf16 v[46:49], v[4:7], v[178:181], v[46:49]
	v_mfma_f32_16x16x32_bf16 v[38:41], v[12:15], v[178:181], v[38:41]
	s_waitcnt lgkmcnt(0)
	v_mfma_f32_16x16x32_bf16 v[0:3], v[4:7], v[186:189], v[0:3]
	v_mfma_f32_16x16x32_bf16 v[4:7], v[8:11], v[182:185], v[226:229]
	v_mfma_f32_16x16x32_bf16 v[4:7], v[12:15], v[186:189], v[4:7]
	v_mfma_f32_16x16x32_bf16 v[30:33], v[16:19], v[166:169], v[66:69]
	v_mfma_f32_16x16x32_bf16 v[66:69], v[20:23], v[170:173], v[30:33]
	v_mfma_f32_16x16x32_bf16 v[30:33], v[150:153], v[166:169], v[58:61]
	v_mfma_f32_16x16x32_bf16 v[58:61], v[154:157], v[170:173], v[30:33]
	v_mfma_f32_16x16x32_bf16 v[30:33], v[16:19], v[174:177], v[50:53]
	v_mfma_f32_16x16x32_bf16 v[8:11], v[16:19], v[158:161], v[86:89]
	v_mfma_f32_16x16x32_bf16 v[50:53], v[20:23], v[178:181], v[30:33]
	v_mfma_f32_16x16x32_bf16 v[30:33], v[150:153], v[174:177], v[42:45]
	v_mfma_f32_16x16x32_bf16 v[16:19], v[16:19], v[182:185], v[34:37]
	v_mfma_f32_16x16x32_bf16 v[8:11], v[20:23], v[162:165], v[8:11]
	v_mfma_f32_16x16x32_bf16 v[12:15], v[150:153], v[158:161], v[74:77]
	v_mfma_f32_16x16x32_bf16 v[42:45], v[154:157], v[178:181], v[30:33]
	v_mfma_f32_16x16x32_bf16 v[16:19], v[20:23], v[186:189], v[16:19]
	v_mfma_f32_16x16x32_bf16 v[20:23], v[150:153], v[182:185], v[26:29]
	v_mfma_f32_16x16x32_bf16 v[12:15], v[154:157], v[162:165], v[12:15]
	v_mfma_f32_16x16x32_bf16 v[20:23], v[154:157], v[186:189], v[20:23]
	s_barrier
	ds_read_b128 v[24:27], v252
	ds_read_b128 v[28:31], v252 offset:1024
	ds_read_b128 v[34:37], v252 offset:2048
	ds_read_b128 v[74:77], v252 offset:3072
	ds_read_b128 v[150:153], v240
	ds_read_b128 v[154:157], v240 offset:1024
	ds_read_b128 v[158:161], v240 offset:2048
	ds_read_b128 v[162:165], v240 offset:3072
	ds_read_b128 v[86:89], v250 offset:32768
	ds_read_b128 v[166:169], v250 offset:33792
	ds_read_b128 v[170:173], v250 offset:34816
	ds_read_b128 v[174:177], v250 offset:35840
	ds_read_b128 v[178:181], v250 offset:36864
	ds_read_b128 v[182:185], v250 offset:37888
	ds_read_b128 v[186:189], v250 offset:38912
	ds_read_b128 v[190:193], v250 offset:39936
	s_add_u32 s8, s8, s30
	s_addc_u32 s9, s9, s31
	s_mov_b32 m0, s55
	s_nop 0
	global_load_lds_dwordx4 v245, s[8:9]
	s_add_u32 s8, s8, s28
	s_addc_u32 s9, s9, s29
	s_mov_b32 m0, s56
	s_nop 0
	global_load_lds_dwordx4 v245, s[8:9]
	s_waitcnt vmcnt(8)
	s_waitcnt lgkmcnt(0)
	s_barrier
	s_waitcnt lgkmcnt(7)
	v_mfma_f32_16x16x32_bf16 v[142:145], v[24:27], v[86:89], v[142:145]
	v_mfma_f32_16x16x32_bf16 v[134:137], v[34:37], v[86:89], v[134:137]
	s_waitcnt lgkmcnt(5)
	v_mfma_f32_16x16x32_bf16 v[126:129], v[24:27], v[170:173], v[126:129]
	v_mfma_f32_16x16x32_bf16 v[118:121], v[34:37], v[170:173], v[118:121]
	s_waitcnt lgkmcnt(3)
	v_mfma_f32_16x16x32_bf16 v[110:113], v[24:27], v[178:181], v[110:113]
	v_mfma_f32_16x16x32_bf16 v[102:105], v[34:37], v[178:181], v[102:105]
	s_waitcnt lgkmcnt(1)
	v_mfma_f32_16x16x32_bf16 v[94:97], v[24:27], v[186:189], v[94:97]
	v_mfma_f32_16x16x32_bf16 v[82:85], v[34:37], v[186:189], v[82:85]
	v_mfma_f32_16x16x32_bf16 v[142:145], v[28:31], v[166:169], v[142:145]
	v_mfma_f32_16x16x32_bf16 v[134:137], v[74:77], v[166:169], v[134:137]
	v_mfma_f32_16x16x32_bf16 v[126:129], v[28:31], v[174:177], v[126:129]
	v_mfma_f32_16x16x32_bf16 v[118:121], v[74:77], v[174:177], v[118:121]
	v_mfma_f32_16x16x32_bf16 v[110:113], v[28:31], v[182:185], v[110:113]
	v_mfma_f32_16x16x32_bf16 v[102:105], v[74:77], v[182:185], v[102:105]
	s_waitcnt lgkmcnt(0)
	v_mfma_f32_16x16x32_bf16 v[94:97], v[28:31], v[190:193], v[94:97]
	v_mfma_f32_16x16x32_bf16 v[82:85], v[74:77], v[190:193], v[82:85]
	v_mfma_f32_16x16x32_bf16 v[146:149], v[150:153], v[86:89], v[146:149]
	v_mfma_f32_16x16x32_bf16 v[86:89], v[158:161], v[86:89], v[138:141]
	v_mfma_f32_16x16x32_bf16 v[138:141], v[162:165], v[166:169], v[86:89]
	v_mfma_f32_16x16x32_bf16 v[86:89], v[150:153], v[170:173], v[130:133]
	v_mfma_f32_16x16x32_bf16 v[130:133], v[154:157], v[174:177], v[86:89]
	v_mfma_f32_16x16x32_bf16 v[86:89], v[158:161], v[170:173], v[122:125]
	v_mfma_f32_16x16x32_bf16 v[122:125], v[162:165], v[174:177], v[86:89]
	v_mfma_f32_16x16x32_bf16 v[86:89], v[150:153], v[178:181], v[114:117]
	v_mfma_f32_16x16x32_bf16 v[114:117], v[154:157], v[182:185], v[86:89]
	v_mfma_f32_16x16x32_bf16 v[86:89], v[158:161], v[178:181], v[106:109]
	v_mfma_f32_16x16x32_bf16 v[106:109], v[162:165], v[182:185], v[86:89]
	v_mfma_f32_16x16x32_bf16 v[86:89], v[150:153], v[186:189], v[98:101]
	v_mfma_f32_16x16x32_bf16 v[98:101], v[154:157], v[190:193], v[86:89]
	v_mfma_f32_16x16x32_bf16 v[86:89], v[158:161], v[186:189], v[90:93]
	v_mfma_f32_16x16x32_bf16 v[146:149], v[154:157], v[166:169], v[146:149]
	v_mfma_f32_16x16x32_bf16 v[90:93], v[162:165], v[190:193], v[86:89]
	s_barrier
; #define PG8_STAGE(bufoff, gbase, voff) do { glds_s((const char*)(gbase), (voff), ldsb + (bufoff)); glds_s((const char*)(gbase) + rstep, (voff), ldsb + (bufoff) + 8192u); } while (0)
; #define PG8_LDA(dst, b, h) do { _Pragma("unroll") for (int m = 0; m < 4; ++m) _Pragma("unroll") for (int k = 0; k < 2; ++k) dst[m][k] = *(const LAS bf16x8*)(lds + PG8_SA(b, h) + aoff + m * 2048 + k * 1024); } while (0)
; #define PG8_WAIT_V(n) asm volatile("s_waitcnt vmcnt(" #n ")" ::: "memory")
; #define PG8_WAIT_L(n) asm volatile("s_waitcnt lgkmcnt(" #n ")" ::: "memory")
; template <class Epi, class Sched>
; __device__ __forceinline__ void gemm_phase(LAS unsigned char* lds, const Gemm g, const Sched& S, const Epi& E, const int tid) {
;     ...
;         for (int t = 0; t < nt; t += 2) {
;             const bool last = (t == nt - 2);
;             const char* a1 = cA + (size_t)(t + 1) * kstep;
;             const char* a2 = last ? nA : cA + (size_t)(t + 2) * kstep; const char* b2 = last ? nB : cB + (size_t)(t + 2) * kstep;
;             const char* a3 = a2 + kstep; const char* b3 = b2 + kstep;
;             const bool relax = (t == 0) && (ui > 0);
;             PG8_LDB(B0, 0, 0); PG8_LDB(B1, 0, 1); PG8_SCHED; PG8_LDA(At, 0, 0); if (!relax) PG8_STAGE(PG8_SA(1, 1), a1 + hstep, voffA);
;             if (relax) PG8_WAIT_V(16); else PG8_WAIT_V(8);
;             PG8_WAIT_L(0); PG8_BAR; PG8_MMA(0, 0, At, B0); PG8_MMA(0, 1, At, B1); PG8_BAR; PG8_SCHED;
;             PG8_LDA(At, 0, 1); PG8_STAGE(PG8_SB(0, 0), b2, voffB); PG8_STAGE(PG8_SB(0, 1), b2 + hstep, voffB); PG8_STAGE(PG8_SA(0, 0), a2, voffA);
;             if (relax) PG8_WAIT_V(16); else PG8_WAIT_V(8);
;             PG8_WAIT_L(0); PG8_BAR; PG8_MMA(1, 0, At, B0); PG8_MMA(1, 1, At, B1); PG8_BAR; PG8_SCHED;
;             PG8_LDB(B0, 1, 0); PG8_LDB(B1, 1, 1); PG8_SCHED; PG8_LDA(At, 1, 0); PG8_STAGE(PG8_SA(0, 1), a2 + hstep, voffA);
;             if (relax) PG8_WAIT_V(16); else PG8_WAIT_V(8);
;             PG8_WAIT_L(0); PG8_BAR; PG8_MMA(0, 0, At, B0); PG8_MMA(0, 1, At, B1); PG8_BAR; PG8_SCHED;
;             PG8_LDA(At, 1, 1); PG8_STAGE(PG8_SB(1, 0), b3, voffB); PG8_STAGE(PG8_SB(1, 1), b3 + hstep, voffB); PG8_STAGE(PG8_SA(1, 0), a3, voffA);
;             PG8_WAIT_V(8); PG8_WAIT_L(0); PG8_BAR; PG8_MMA(1, 0, At, B0); PG8_MMA(1, 1, At, B1); PG8_BAR; PG8_SCHED;
;         }
;         if (wr == 0) PG8_BAR;
	ds_read_b128 v[166:169], v250 offset:49152
	ds_read_b128 v[170:173], v250 offset:50176
	ds_read_b128 v[174:177], v250 offset:51200
	ds_read_b128 v[178:181], v250 offset:52224
	ds_read_b128 v[182:185], v250 offset:53248
	ds_read_b128 v[186:189], v250 offset:54272
	ds_read_b128 v[190:193], v250 offset:55296
	ds_read_b128 v[194:197], v250 offset:56320
	s_mov_b32 m0, s59
	s_nop 0
	global_load_lds_dwordx4 v246, s[6:7]
	s_add_u32 s6, s6, s28
	s_addc_u32 s7, s7, s29
	s_mov_b32 m0, s60
	s_nop 0
	global_load_lds_dwordx4 v246, s[6:7]
	s_add_u32 s6, s40, 0x80
	s_addc_u32 s7, s41, 0
	s_mov_b32 m0, s63
	s_nop 0
	global_load_lds_dwordx4 v246, s[6:7]
	s_add_u32 s6, s6, s28
	s_addc_u32 s7, s7, s29
	s_mov_b32 m0, s64
	s_nop 0
	global_load_lds_dwordx4 v246, s[6:7]
	s_mov_b32 m0, s61
	s_nop 0
	global_load_lds_dwordx4 v245, s[0:1]
	s_add_u32 s0, s0, s28
	s_addc_u32 s1, s1, s29
	s_mov_b32 m0, s62
	s_nop 0
	global_load_lds_dwordx4 v245, s[0:1]
	s_waitcnt vmcnt(8)
	s_waitcnt lgkmcnt(0)
	s_barrier
	s_waitcnt lgkmcnt(7)
	v_mfma_f32_16x16x32_bf16 v[78:81], v[24:27], v[166:169], v[78:81]
	s_waitcnt lgkmcnt(5)
	v_mfma_f32_16x16x32_bf16 v[62:65], v[24:27], v[174:177], v[62:65]
	s_waitcnt lgkmcnt(3)
	v_mfma_f32_16x16x32_bf16 v[46:49], v[24:27], v[182:185], v[46:49]
	s_waitcnt lgkmcnt(1)
	v_mfma_f32_16x16x32_bf16 v[0:3], v[24:27], v[190:193], v[0:3]
	v_mfma_f32_16x16x32_bf16 v[78:81], v[28:31], v[170:173], v[78:81]
	v_mfma_f32_16x16x32_bf16 v[70:73], v[34:37], v[166:169], v[70:73]
	v_mfma_f32_16x16x32_bf16 v[62:65], v[28:31], v[178:181], v[62:65]
	v_mfma_f32_16x16x32_bf16 v[54:57], v[34:37], v[174:177], v[54:57]
	v_mfma_f32_16x16x32_bf16 v[46:49], v[28:31], v[186:189], v[46:49]
	v_mfma_f32_16x16x32_bf16 v[38:41], v[34:37], v[182:185], v[38:41]
	s_waitcnt lgkmcnt(0)
	v_mfma_f32_16x16x32_bf16 v[30:33], v[28:31], v[194:197], v[0:3]
	v_mfma_f32_16x16x32_bf16 v[0:3], v[34:37], v[190:193], v[4:7]
	v_mfma_f32_16x16x32_bf16 v[70:73], v[74:77], v[170:173], v[70:73]
	v_mfma_f32_16x16x32_bf16 v[54:57], v[74:77], v[178:181], v[54:57]
	v_mfma_f32_16x16x32_bf16 v[38:41], v[74:77], v[186:189], v[38:41]
	v_mfma_f32_16x16x32_bf16 v[226:229], v[74:77], v[194:197], v[0:3]
	v_mfma_f32_16x16x32_bf16 v[0:3], v[150:153], v[166:169], v[8:11]
	v_mfma_f32_16x16x32_bf16 v[86:89], v[154:157], v[170:173], v[0:3]
	v_mfma_f32_16x16x32_bf16 v[0:3], v[158:161], v[166:169], v[12:15]
	v_mfma_f32_16x16x32_bf16 v[74:77], v[162:165], v[170:173], v[0:3]
	v_mfma_f32_16x16x32_bf16 v[0:3], v[150:153], v[174:177], v[66:69]
	v_mfma_f32_16x16x32_bf16 v[66:69], v[154:157], v[178:181], v[0:3]
	v_mfma_f32_16x16x32_bf16 v[0:3], v[158:161], v[174:177], v[58:61]
	v_mfma_f32_16x16x32_bf16 v[58:61], v[162:165], v[178:181], v[0:3]
	v_mfma_f32_16x16x32_bf16 v[0:3], v[150:153], v[182:185], v[50:53]
	v_mfma_f32_16x16x32_bf16 v[50:53], v[154:157], v[186:189], v[0:3]
	v_mfma_f32_16x16x32_bf16 v[0:3], v[158:161], v[182:185], v[42:45]
	v_mfma_f32_16x16x32_bf16 v[42:45], v[162:165], v[186:189], v[0:3]
	v_mfma_f32_16x16x32_bf16 v[0:3], v[150:153], v[190:193], v[16:19]
	v_mfma_f32_16x16x32_bf16 v[34:37], v[154:157], v[194:197], v[0:3]
	v_mfma_f32_16x16x32_bf16 v[0:3], v[158:161], v[190:193], v[20:23]
	v_mfma_f32_16x16x32_bf16 v[26:29], v[162:165], v[194:197], v[0:3]
	s_barrier
	s_add_u32 s2, s2, 0x100
	s_addc_u32 s3, s3, 0
	s_add_i32 s0, s97, 2
	s_add_u32 s85, s85, 0x100
	s_addc_u32 s96, s96, 0
	s_cmp_ge_u32 s97, s42
	s_mov_b32 s97, s0
	s_cbranch_scc0 .LBB0_200
	s_and_b64 vcc, exec, s[68:69]
	s_cbranch_vccz .LBB0_203
	s_barrier

; #define LAS __attribute__((address_space(3)))
; #define PG8_WAIT_V(n) asm volatile("s_waitcnt vmcnt(" #n ")" ::: "memory")
; #define PG8_BAR __builtin_amdgcn_s_barrier()
; template <class Epi, class Sched>
; __device__ __forceinline__ void gemm_phase(LAS unsigned char* lds, const Gemm g, const Sched& S, const Epi& E, const int tid) {
;     ...
;     PG8_WAIT_V(0);
;     PG8_BAR;
; __global__ void __launch_bounds__(512, 2) __attribute__((amdgpu_waves_per_eu(2, 2))) mk_fwd(Args a_) {
;     ...
;         if (ph + 1 < hi) {
;             xcd_barrier((unsigned*)(ws + WS_CTL) + CW_BAR, (volatile LAS unsigned*)(lds + MISC_OFF));
.LBB0_487:
	s_setprio 0
	v_readlane_b32 s30, v253, 22
	v_readlane_b32 s31, v253, 23
	s_waitcnt vmcnt(0)
	s_barrier
	s_load_dwordx2 s[28:29], s[30:31], 0xa8
	v_readlane_b32 s54, v253, 7
	v_readlane_b32 s56, v253, 9
	v_readlane_b32 s53, v253, 6
	v_readlane_b32 s55, v253, 8
	v_readlane_b32 s57, v253, 10
	v_readlane_b32 s58, v253, 11
	v_readlane_b32 s52, v253, 13
	v_readlane_b32 s62, v253, 27
	v_readlane_b32 s64, v253, 36
	v_readlane_b32 s34, v253, 24
	v_readlane_b32 s59, v253, 12
	v_readlane_b32 s63, v253, 28
	v_readlane_b32 s65, v253, 37
	v_readlane_b32 s35, v253, 25
